# barrier 3 split-phase: chunk preparation starts when the row-panel counters of its in-projection tiles (published write-through) are complete; the barrier-3 wait is deferred to the start of phase 4
# speedup vs baseline: 1.0113x; 1.0014x over previous
.LBB0_198:
	s_andn2_b64 vcc, exec, s[4:5]
	s_cbranch_vccnz .LBB0_200
	s_mov_b64 s[84:85], exec
	v_readlane_b32 s86, v254, 6
	s_nop 3
	s_mov_b32 exec_lo, s86
	s_mov_b32 exec_hi, 0
	s_cbranch_execz .Lp2pub_join
	s_and_b32 s86, s64, 7
	s_lshl_b32 s86, s86, 3
	s_bfe_u32 s87, s64, 0x30003
	s_or_b32 s86, s86, s87
	s_lshl_b32 s86, s86, 8
	s_add_i32 s86, s86, 0x8000
	s_cmpk_lt_u32 s64, 0x80
	s_cselect_b32 s87, 2, 1
	v_mov_b32_e32 v252, s86
	v_mov_b32_e32 v253, s87
	global_atomic_add v252, v253, s[82:83]
.Lp2pub_join:
	s_mov_b64 exec, s[84:85]
	v_lshlrev_b32_e32 v163, 7, v162
	v_lshl_or_b32 v138, v161, 5, v163
	v_and_b32_e32 v249, 15, v162
	v_and_b32_e32 v248, 0xfffffff0, v162
	v_lshlrev_b32_e32 v248, 7, v248
	v_lshl_or_b32 v248, v249, 4, v248
	v_lshl_or_b32 v248, v161, 8, v248
	s_add_u32 s98, s82, 0xc00000
	s_addc_u32 s99, s83, 0
	s_add_u32 s100, s82, 0xe00000
	s_addc_u32 s101, s83, 0
	global_load_dwordx4 v[184:187], v248, s[98:99]
	global_load_dwordx4 v[188:191], v248, s[100:101]
	global_load_dwordx4 v[192:195], v248, s[98:99] offset:1024
	global_load_dwordx4 v[196:199], v248, s[100:101] offset:1024
	v_add_u32_e32 v249, 0x800, v248
	global_load_dwordx4 v[200:203], v249, s[98:99]
	global_load_dwordx4 v[204:207], v249, s[100:101]
	global_load_dwordx4 v[208:211], v249, s[98:99] offset:1024
	global_load_dwordx4 v[212:215], v249, s[100:101] offset:1024
	v_add_u32_e32 v250, 0x1000, v248
	global_load_dwordx4 v[216:219], v250, s[98:99]
	global_load_dwordx4 v[220:223], v250, s[100:101]
	global_load_dwordx4 v[224:227], v250, s[98:99] offset:1024
	global_load_dwordx4 v[228:231], v250, s[100:101] offset:1024
	v_add_u32_e32 v251, 0x1800, v248
	global_load_dwordx4 v[232:235], v251, s[98:99]
	global_load_dwordx4 v[236:239], v251, s[100:101]
	global_load_dwordx4 v[240:243], v251, s[98:99] offset:1024
	global_load_dwordx4 v[244:247], v251, s[100:101] offset:1024
	v_lshl_add_u64 v[148:149], s[82:83], 0, v[138:139]
	v_add_co_u32_e32 v150, vcc, s51, v148
	s_cmp_lt_u32 s18, 10
	s_nop 0
	v_addc_co_u32_e32 v151, vcc, 0, v149, vcc
	v_add_co_u32_e32 v152, vcc, s50, v148
	s_nop 0
	v_addc_co_u32_e32 v153, vcc, 0, v149, vcc
	s_cselect_b64 vcc, -1, 0
	v_cndmask_b32_e32 v138, 1.0, v160, vcc
	v_add_co_u32_e64 v154, s[4:5], s48, v148
	v_mov_b32_e32 v181, v139
	s_nop 0
	v_addc_co_u32_e64 v155, s[4:5], 0, v149, s[4:5]
	v_add_co_u32_e64 v178, s[4:5], s49, v148
	s_waitcnt vmcnt(12)
	v_pk_mul_f32 v[166:167], v[138:139], v[186:187] op_sel_hi:[0,1]
	v_pk_mul_f32 v[164:165], v[138:139], v[184:185] op_sel_hi:[0,1]
	v_addc_co_u32_e64 v179, s[4:5], 0, v149, s[4:5]
	v_pk_mul_f32 v[170:171], v[138:139], v[190:191] op_sel_hi:[0,1]
	v_pk_mul_f32 v[168:169], v[138:139], v[188:189] op_sel_hi:[0,1]
	v_pk_mul_f32 v[172:173], v[120:121], v[170:171]
	v_pk_mul_f32 v[174:175], v[118:119], v[168:169]
	v_pk_mul_f32 v[168:169], v[126:127], v[168:169]
	v_pk_mul_f32 v[170:171], v[128:129], v[170:171]
	v_pk_fma_f32 v[172:173], v[128:129], v[166:167], v[172:173] neg_lo:[0,0,1] neg_hi:[0,0,1]
	v_pk_fma_f32 v[174:175], v[126:127], v[164:165], v[174:175] neg_lo:[0,0,1] neg_hi:[0,0,1]
	v_pk_fma_f32 v[168:169], v[118:119], v[164:165], v[168:169]
	v_pk_fma_f32 v[166:167], v[120:121], v[166:167], v[170:171]
	v_cvt_pk_bf16_f32 v164, v174, v175
	v_cvt_pk_bf16_f32 v165, v172, v173
	v_cvt_pk_bf16_f32 v168, v168, v169
	s_and_b64 s[4:5], vcc, exec
	v_cvt_pk_bf16_f32 v169, v166, v167
	s_cselect_b32 s4, s47, 0x6000000
	s_lshl_b32 s5, s18, 2
	s_and_b32 s5, s5, 4
	v_lshl_or_b32 v166, v161, 4, s4
	s_or_b32 s4, s11, s5
	v_lshl_or_b32 v166, s4, 21, v166
	v_add_u32_e32 v180, v166, v163
	v_pk_mul_f32 v[166:167], v[138:139], v[194:195] op_sel_hi:[0,1]
	v_pk_mul_f32 v[172:173], v[138:139], v[198:199] op_sel_hi:[0,1]
	v_pk_mul_f32 v[174:175], v[138:139], v[196:197] op_sel_hi:[0,1]
	v_pk_mul_f32 v[170:171], v[138:139], v[192:193] op_sel_hi:[0,1]
	v_pk_mul_f32 v[176:177], v[116:117], v[172:173]
	v_pk_mul_f32 v[182:183], v[114:115], v[174:175]
	v_pk_mul_f32 v[172:173], v[124:125], v[172:173]
	v_pk_mul_f32 v[174:175], v[122:123], v[174:175]
	v_pk_fma_f32 v[176:177], v[124:125], v[166:167], v[176:177] neg_lo:[0,0,1] neg_hi:[0,0,1]
	v_pk_fma_f32 v[182:183], v[122:123], v[170:171], v[182:183] neg_lo:[0,0,1] neg_hi:[0,0,1]
	v_pk_fma_f32 v[172:173], v[116:117], v[166:167], v[172:173]
	v_pk_fma_f32 v[170:171], v[114:115], v[170:171], v[174:175]
	v_cvt_pk_bf16_f32 v166, v182, v183
	v_cvt_pk_bf16_f32 v167, v176, v177
	s_nop 0
	v_cvt_pk_bf16_f32 v170, v170, v171
	v_cvt_pk_bf16_f32 v171, v172, v173
	global_store_dwordx4 v180, v[164:167], s[82:83]
	global_store_dwordx4 v180, v[168:171], s[82:83] offset:64
	v_add_u32_e32 v252, 0x4000, v248
	global_load_dwordx4 v[184:187], v252, s[98:99]
	global_load_dwordx4 v[188:191], v252, s[100:101]
	global_load_dwordx4 v[192:195], v252, s[98:99] offset:1024
	global_load_dwordx4 v[196:199], v252, s[100:101] offset:1024
	s_nop 0
	s_waitcnt vmcnt(14)
	v_pk_mul_f32 v[166:167], v[138:139], v[202:203] op_sel_hi:[0,1]
	v_pk_mul_f32 v[164:165], v[138:139], v[200:201] op_sel_hi:[0,1]
	v_pk_mul_f32 v[168:169], v[138:139], v[204:205] op_sel_hi:[0,1]
	v_pk_mul_f32 v[170:171], v[138:139], v[206:207] op_sel_hi:[0,1]
	v_pk_mul_f32 v[174:175], v[102:103], v[168:169]
	v_pk_mul_f32 v[176:177], v[104:105], v[166:167]
	v_pk_mul_f32 v[182:183], v[102:103], v[164:165]
	v_pk_mul_f32 v[172:173], v[104:105], v[170:171]
	v_pk_fma_f32 v[164:165], v[110:111], v[164:165], v[174:175] neg_lo:[0,0,1] neg_hi:[0,0,1]
	v_pk_fma_f32 v[170:171], v[112:113], v[170:171], v[176:177]
	v_pk_fma_f32 v[168:169], v[110:111], v[168:169], v[182:183]
	v_pk_fma_f32 v[166:167], v[112:113], v[166:167], v[172:173] neg_lo:[0,0,1] neg_hi:[0,0,1]
	v_cvt_pk_bf16_f32 v164, v164, v165
	s_nop 0
	v_cvt_pk_bf16_f32 v165, v166, v167
	v_cvt_pk_bf16_f32 v168, v168, v169
	v_cvt_pk_bf16_f32 v169, v170, v171
	v_pk_mul_f32 v[154:155], v[138:139], v[210:211] op_sel_hi:[0,1]
	v_pk_mul_f32 v[166:167], v[138:139], v[208:209] op_sel_hi:[0,1]
	v_pk_mul_f32 v[170:171], v[138:139], v[214:215] op_sel_hi:[0,1]
	v_pk_mul_f32 v[172:173], v[138:139], v[212:213] op_sel_hi:[0,1]
	v_pk_mul_f32 v[174:175], v[100:101], v[170:171]
	v_pk_mul_f32 v[176:177], v[98:99], v[172:173]
	v_pk_mul_f32 v[170:171], v[108:109], v[170:171]
	v_pk_mul_f32 v[172:173], v[106:107], v[172:173]
	v_pk_fma_f32 v[174:175], v[108:109], v[154:155], v[174:175] neg_lo:[0,0,1] neg_hi:[0,0,1]
	v_pk_fma_f32 v[176:177], v[106:107], v[166:167], v[176:177] neg_lo:[0,0,1] neg_hi:[0,0,1]
	v_pk_fma_f32 v[154:155], v[100:101], v[154:155], v[170:171]
	v_pk_fma_f32 v[170:171], v[98:99], v[166:167], v[172:173]
	v_cvt_pk_bf16_f32 v166, v176, v177
	v_cvt_pk_bf16_f32 v167, v174, v175
	s_nop 0
	v_cvt_pk_bf16_f32 v170, v170, v171
	v_cvt_pk_bf16_f32 v171, v154, v155
	global_store_dwordx4 v180, v[164:167], s[82:83] offset:2048
	global_store_dwordx4 v180, v[168:171], s[82:83] offset:2112
	v_add_u32_e32 v252, 0x4800, v248
	global_load_dwordx4 v[200:203], v252, s[98:99]
	global_load_dwordx4 v[204:207], v252, s[100:101]
	global_load_dwordx4 v[208:211], v252, s[98:99] offset:1024
	global_load_dwordx4 v[212:215], v252, s[100:101] offset:1024
	s_nop 0
	s_waitcnt vmcnt(16)
	v_pk_mul_f32 v[164:165], v[138:139], v[216:217] op_sel_hi:[0,1]
	v_pk_mul_f32 v[168:169], v[138:139], v[220:221] op_sel_hi:[0,1]
	v_pk_mul_f32 v[154:155], v[138:139], v[218:219] op_sel_hi:[0,1]
	v_pk_mul_f32 v[166:167], v[138:139], v[222:223] op_sel_hi:[0,1]
	v_pk_mul_f32 v[172:173], v[86:87], v[168:169]
	v_pk_mul_f32 v[176:177], v[86:87], v[164:165]
	v_pk_mul_f32 v[170:171], v[88:89], v[166:167]
	v_pk_mul_f32 v[174:175], v[88:89], v[154:155]
	v_pk_fma_f32 v[164:165], v[94:95], v[164:165], v[172:173] neg_lo:[0,0,1] neg_hi:[0,0,1]
	v_pk_fma_f32 v[168:169], v[94:95], v[168:169], v[176:177]
	v_pk_fma_f32 v[154:155], v[96:97], v[154:155], v[170:171] neg_lo:[0,0,1] neg_hi:[0,0,1]
	v_pk_fma_f32 v[166:167], v[96:97], v[166:167], v[174:175]
	v_cvt_pk_bf16_f32 v164, v164, v165
	v_cvt_pk_bf16_f32 v165, v154, v155
	v_cvt_pk_bf16_f32 v168, v168, v169
	v_lshl_add_u64 v[154:155], s[82:83], 0, v[180:181]
	v_cvt_pk_bf16_f32 v169, v166, v167
	v_add_co_u32_e32 v178, vcc, s45, v154
	v_pk_mul_f32 v[166:167], v[138:139], v[226:227] op_sel_hi:[0,1]
	v_pk_mul_f32 v[172:173], v[138:139], v[230:231] op_sel_hi:[0,1]
	v_pk_mul_f32 v[174:175], v[138:139], v[228:229] op_sel_hi:[0,1]
	v_pk_mul_f32 v[170:171], v[138:139], v[224:225] op_sel_hi:[0,1]
	v_pk_mul_f32 v[176:177], v[84:85], v[172:173]
	v_pk_mul_f32 v[180:181], v[82:83], v[174:175]
	v_pk_mul_f32 v[172:173], v[92:93], v[172:173]
	v_pk_mul_f32 v[174:175], v[90:91], v[174:175]
	v_addc_co_u32_e32 v179, vcc, 0, v155, vcc
	v_pk_fma_f32 v[176:177], v[92:93], v[166:167], v[176:177] neg_lo:[0,0,1] neg_hi:[0,0,1]
	v_pk_fma_f32 v[180:181], v[90:91], v[170:171], v[180:181] neg_lo:[0,0,1] neg_hi:[0,0,1]
	v_pk_fma_f32 v[172:173], v[84:85], v[166:167], v[172:173]
	v_pk_fma_f32 v[170:171], v[82:83], v[170:171], v[174:175]
	v_cvt_pk_bf16_f32 v166, v180, v181
	v_cvt_pk_bf16_f32 v167, v176, v177
	s_nop 0
	v_cvt_pk_bf16_f32 v170, v170, v171
	v_cvt_pk_bf16_f32 v171, v172, v173
	global_store_dwordx4 v[178:179], v[164:167], off
	global_store_dwordx4 v[178:179], v[168:171], off offset:64
	v_add_u32_e32 v252, 0x5000, v248
	global_load_dwordx4 v[216:219], v252, s[98:99]
	global_load_dwordx4 v[220:223], v252, s[100:101]
	global_load_dwordx4 v[224:227], v252, s[98:99] offset:1024
	global_load_dwordx4 v[228:231], v252, s[100:101] offset:1024
	s_nop 0
	s_waitcnt vmcnt(18)
	v_pk_mul_f32 v[166:167], v[138:139], v[234:235] op_sel_hi:[0,1]
	v_pk_mul_f32 v[164:165], v[138:139], v[232:233] op_sel_hi:[0,1]
	v_pk_mul_f32 v[168:169], v[138:139], v[236:237] op_sel_hi:[0,1]
	v_pk_mul_f32 v[170:171], v[138:139], v[238:239] op_sel_hi:[0,1]
	v_pk_mul_f32 v[174:175], v[70:71], v[168:169]
	v_pk_mul_f32 v[176:177], v[72:73], v[166:167]
	v_pk_mul_f32 v[180:181], v[70:71], v[164:165]
	v_pk_mul_f32 v[172:173], v[72:73], v[170:171]
	v_pk_fma_f32 v[164:165], v[78:79], v[164:165], v[174:175] neg_lo:[0,0,1] neg_hi:[0,0,1]
	v_pk_fma_f32 v[170:171], v[80:81], v[170:171], v[176:177]
	v_pk_fma_f32 v[168:169], v[78:79], v[168:169], v[180:181]
	v_pk_fma_f32 v[166:167], v[80:81], v[166:167], v[172:173] neg_lo:[0,0,1] neg_hi:[0,0,1]
	v_cvt_pk_bf16_f32 v164, v164, v165
	s_nop 0
	v_cvt_pk_bf16_f32 v165, v166, v167
	v_cvt_pk_bf16_f32 v168, v168, v169
	v_cvt_pk_bf16_f32 v169, v170, v171
	v_add_co_u32_e32 v150, vcc, s55, v148
	v_pk_mul_f32 v[152:153], v[138:139], v[242:243] op_sel_hi:[0,1]
	v_pk_mul_f32 v[166:167], v[138:139], v[240:241] op_sel_hi:[0,1]
	v_pk_mul_f32 v[170:171], v[138:139], v[246:247] op_sel_hi:[0,1]
	v_pk_mul_f32 v[172:173], v[138:139], v[244:245] op_sel_hi:[0,1]
	v_pk_mul_f32 v[174:175], v[68:69], v[170:171]
	v_pk_mul_f32 v[176:177], v[66:67], v[172:173]
	v_pk_mul_f32 v[170:171], v[76:77], v[170:171]
	v_pk_mul_f32 v[172:173], v[74:75], v[172:173]
	v_addc_co_u32_e32 v151, vcc, 0, v149, vcc
	v_pk_fma_f32 v[174:175], v[76:77], v[152:153], v[174:175] neg_lo:[0,0,1] neg_hi:[0,0,1]
	v_pk_fma_f32 v[176:177], v[74:75], v[166:167], v[176:177] neg_lo:[0,0,1] neg_hi:[0,0,1]
	v_pk_fma_f32 v[152:153], v[68:69], v[152:153], v[170:171]
	v_pk_fma_f32 v[170:171], v[66:67], v[166:167], v[172:173]
	v_cvt_pk_bf16_f32 v166, v176, v177
	v_cvt_pk_bf16_f32 v167, v174, v175
	s_nop 0
	v_cvt_pk_bf16_f32 v170, v170, v171
	v_cvt_pk_bf16_f32 v171, v152, v153
	global_store_dwordx4 v[178:179], v[164:167], off offset:2048
	global_store_dwordx4 v[178:179], v[168:171], off offset:2112
	v_add_u32_e32 v252, 0x5800, v248
	global_load_dwordx4 v[232:235], v252, s[98:99]
	global_load_dwordx4 v[236:239], v252, s[100:101]
	global_load_dwordx4 v[240:243], v252, s[98:99] offset:1024
	global_load_dwordx4 v[244:247], v252, s[100:101] offset:1024
	v_add_co_u32_e32 v152, vcc, s54, v148
	s_nop 0
	v_addc_co_u32_e32 v153, vcc, 0, v149, vcc
	v_add_co_u32_e32 v178, vcc, s52, v148
	s_waitcnt vmcnt(18)
	v_pk_mul_f32 v[166:167], v[138:139], v[186:187] op_sel_hi:[0,1]
	v_addc_co_u32_e32 v179, vcc, 0, v149, vcc
	v_pk_mul_f32 v[170:171], v[138:139], v[190:191] op_sel_hi:[0,1]
	v_pk_mul_f32 v[168:169], v[138:139], v[188:189] op_sel_hi:[0,1]
	v_pk_mul_f32 v[164:165], v[138:139], v[184:185] op_sel_hi:[0,1]
	v_pk_mul_f32 v[172:173], v[56:57], v[170:171]
	v_pk_mul_f32 v[174:175], v[54:55], v[168:169]
	v_pk_mul_f32 v[168:169], v[62:63], v[168:169]
	v_add_co_u32_e32 v180, vcc, s53, v148
	v_pk_mul_f32 v[170:171], v[64:65], v[170:171]
	v_pk_fma_f32 v[172:173], v[64:65], v[166:167], v[172:173] neg_lo:[0,0,1] neg_hi:[0,0,1]
	v_pk_fma_f32 v[174:175], v[62:63], v[164:165], v[174:175] neg_lo:[0,0,1] neg_hi:[0,0,1]
	v_pk_fma_f32 v[168:169], v[54:55], v[164:165], v[168:169]
	v_addc_co_u32_e32 v181, vcc, 0, v149, vcc
	v_pk_fma_f32 v[166:167], v[56:57], v[166:167], v[170:171]
	v_cvt_pk_bf16_f32 v164, v174, v175
	v_cvt_pk_bf16_f32 v165, v172, v173
	v_cvt_pk_bf16_f32 v168, v168, v169
	v_add_co_u32_e32 v182, vcc, s38, v154
	v_cvt_pk_bf16_f32 v169, v166, v167
	v_addc_co_u32_e32 v183, vcc, 0, v155, vcc
	v_add_co_u32_e32 v148, vcc, s46, v154
	v_pk_mul_f32 v[166:167], v[138:139], v[192:193] op_sel_hi:[0,1]
	v_addc_co_u32_e32 v149, vcc, 0, v155, vcc
	v_pk_mul_f32 v[154:155], v[138:139], v[194:195] op_sel_hi:[0,1]
	v_pk_mul_f32 v[170:171], v[138:139], v[198:199] op_sel_hi:[0,1]
	v_pk_mul_f32 v[172:173], v[138:139], v[196:197] op_sel_hi:[0,1]
	v_pk_mul_f32 v[174:175], v[52:53], v[170:171]
	v_pk_mul_f32 v[176:177], v[50:51], v[172:173]
	v_pk_mul_f32 v[170:171], v[60:61], v[170:171]
	v_pk_mul_f32 v[172:173], v[58:59], v[172:173]
	v_pk_fma_f32 v[174:175], v[60:61], v[154:155], v[174:175] neg_lo:[0,0,1] neg_hi:[0,0,1]
	v_pk_fma_f32 v[176:177], v[58:59], v[166:167], v[176:177] neg_lo:[0,0,1] neg_hi:[0,0,1]
	v_pk_fma_f32 v[154:155], v[52:53], v[154:155], v[170:171]
	v_pk_fma_f32 v[170:171], v[50:51], v[166:167], v[172:173]
	v_cvt_pk_bf16_f32 v166, v176, v177
	v_cvt_pk_bf16_f32 v167, v174, v175
	s_nop 0
	v_cvt_pk_bf16_f32 v170, v170, v171
	v_cvt_pk_bf16_f32 v171, v154, v155
	global_store_dwordx4 v[148:149], v[164:167], off offset:-4096
	global_store_dwordx4 v[182:183], v[168:171], off offset:64
	s_nop 0
	s_waitcnt vmcnt(14)
	v_pk_mul_f32 v[164:165], v[138:139], v[200:201] op_sel_hi:[0,1]
	v_pk_mul_f32 v[168:169], v[138:139], v[204:205] op_sel_hi:[0,1]
	v_pk_mul_f32 v[154:155], v[138:139], v[202:203] op_sel_hi:[0,1]
	v_pk_mul_f32 v[166:167], v[138:139], v[206:207] op_sel_hi:[0,1]
	v_pk_mul_f32 v[172:173], v[38:39], v[168:169]
	v_pk_mul_f32 v[176:177], v[38:39], v[164:165]
	v_pk_mul_f32 v[170:171], v[40:41], v[166:167]
	v_pk_mul_f32 v[174:175], v[40:41], v[154:155]
	v_pk_fma_f32 v[164:165], v[46:47], v[164:165], v[172:173] neg_lo:[0,0,1] neg_hi:[0,0,1]
	v_pk_fma_f32 v[168:169], v[46:47], v[168:169], v[176:177]
	v_pk_fma_f32 v[154:155], v[48:49], v[154:155], v[170:171] neg_lo:[0,0,1] neg_hi:[0,0,1]
	v_pk_fma_f32 v[166:167], v[48:49], v[166:167], v[174:175]
	v_cvt_pk_bf16_f32 v164, v164, v165
	v_cvt_pk_bf16_f32 v165, v154, v155
	v_cvt_pk_bf16_f32 v168, v168, v169
	s_nop 0
	v_cvt_pk_bf16_f32 v169, v166, v167
	v_pk_mul_f32 v[154:155], v[138:139], v[210:211] op_sel_hi:[0,1]
	v_pk_mul_f32 v[166:167], v[138:139], v[208:209] op_sel_hi:[0,1]
	v_pk_mul_f32 v[170:171], v[138:139], v[214:215] op_sel_hi:[0,1]
	v_pk_mul_f32 v[172:173], v[138:139], v[212:213] op_sel_hi:[0,1]
	v_pk_mul_f32 v[174:175], v[36:37], v[170:171]
	v_pk_mul_f32 v[176:177], v[34:35], v[172:173]
	v_pk_mul_f32 v[170:171], v[44:45], v[170:171]
	v_pk_mul_f32 v[172:173], v[42:43], v[172:173]
	v_pk_fma_f32 v[174:175], v[44:45], v[154:155], v[174:175] neg_lo:[0,0,1] neg_hi:[0,0,1]
	v_pk_fma_f32 v[176:177], v[42:43], v[166:167], v[176:177] neg_lo:[0,0,1] neg_hi:[0,0,1]
	v_pk_fma_f32 v[154:155], v[36:37], v[154:155], v[170:171]
	v_pk_fma_f32 v[170:171], v[34:35], v[166:167], v[172:173]
	v_cvt_pk_bf16_f32 v166, v176, v177
	v_cvt_pk_bf16_f32 v167, v174, v175
	s_nop 0
	v_cvt_pk_bf16_f32 v170, v170, v171
	v_cvt_pk_bf16_f32 v171, v154, v155
	global_store_dwordx4 v[182:183], v[164:167], off offset:2048
	global_store_dwordx4 v[182:183], v[168:171], off offset:2112
	s_nop 0
	s_waitcnt vmcnt(10)
	v_pk_mul_f32 v[164:165], v[138:139], v[216:217] op_sel_hi:[0,1]
	v_pk_mul_f32 v[168:169], v[138:139], v[220:221] op_sel_hi:[0,1]
	v_pk_mul_f32 v[154:155], v[138:139], v[218:219] op_sel_hi:[0,1]
	v_pk_mul_f32 v[166:167], v[138:139], v[222:223] op_sel_hi:[0,1]
	v_pk_mul_f32 v[172:173], v[22:23], v[168:169]
	v_pk_mul_f32 v[176:177], v[22:23], v[164:165]
	v_pk_mul_f32 v[170:171], v[24:25], v[166:167]
	v_pk_mul_f32 v[174:175], v[24:25], v[154:155]
	v_pk_fma_f32 v[164:165], v[30:31], v[164:165], v[172:173] neg_lo:[0,0,1] neg_hi:[0,0,1]
	v_pk_fma_f32 v[168:169], v[30:31], v[168:169], v[176:177]
	v_pk_fma_f32 v[154:155], v[32:33], v[154:155], v[170:171] neg_lo:[0,0,1] neg_hi:[0,0,1]
	v_pk_fma_f32 v[166:167], v[32:33], v[166:167], v[174:175]
	v_cvt_pk_bf16_f32 v164, v164, v165
	v_cvt_pk_bf16_f32 v165, v154, v155
	v_cvt_pk_bf16_f32 v168, v168, v169
	s_nop 0
	v_cvt_pk_bf16_f32 v169, v166, v167
	v_pk_mul_f32 v[154:155], v[138:139], v[226:227] op_sel_hi:[0,1]
	v_pk_mul_f32 v[166:167], v[138:139], v[224:225] op_sel_hi:[0,1]
	v_pk_mul_f32 v[170:171], v[138:139], v[230:231] op_sel_hi:[0,1]
	v_pk_mul_f32 v[172:173], v[138:139], v[228:229] op_sel_hi:[0,1]
	v_pk_mul_f32 v[174:175], v[20:21], v[170:171]
	v_pk_mul_f32 v[176:177], v[18:19], v[172:173]
	v_pk_mul_f32 v[170:171], v[28:29], v[170:171]
	v_pk_mul_f32 v[172:173], v[26:27], v[172:173]
	v_pk_fma_f32 v[174:175], v[28:29], v[154:155], v[174:175] neg_lo:[0,0,1] neg_hi:[0,0,1]
	v_pk_fma_f32 v[176:177], v[26:27], v[166:167], v[176:177] neg_lo:[0,0,1] neg_hi:[0,0,1]
	v_pk_fma_f32 v[154:155], v[20:21], v[154:155], v[170:171]
	v_pk_fma_f32 v[170:171], v[18:19], v[166:167], v[172:173]
	v_cvt_pk_bf16_f32 v166, v176, v177
	v_cvt_pk_bf16_f32 v167, v174, v175
	s_nop 0
	v_cvt_pk_bf16_f32 v170, v170, v171
	v_cvt_pk_bf16_f32 v171, v154, v155
	global_store_dwordx4 v[148:149], v[164:167], off
	global_store_dwordx4 v[148:149], v[168:171], off offset:64
	s_nop 0
	s_waitcnt vmcnt(6)
	v_pk_mul_f32 v[164:165], v[138:139], v[232:233] op_sel_hi:[0,1]
	v_pk_mul_f32 v[168:169], v[138:139], v[236:237] op_sel_hi:[0,1]
	v_pk_mul_f32 v[154:155], v[138:139], v[234:235] op_sel_hi:[0,1]
	v_pk_mul_f32 v[166:167], v[138:139], v[238:239] op_sel_hi:[0,1]
	v_pk_mul_f32 v[172:173], v[6:7], v[168:169]
	v_pk_mul_f32 v[176:177], v[6:7], v[164:165]
	v_pk_mul_f32 v[170:171], v[8:9], v[166:167]
	v_pk_mul_f32 v[174:175], v[8:9], v[154:155]
	v_pk_fma_f32 v[164:165], v[14:15], v[164:165], v[172:173] neg_lo:[0,0,1] neg_hi:[0,0,1]
	v_pk_fma_f32 v[168:169], v[14:15], v[168:169], v[176:177]
	v_pk_fma_f32 v[154:155], v[16:17], v[154:155], v[170:171] neg_lo:[0,0,1] neg_hi:[0,0,1]
	v_pk_fma_f32 v[166:167], v[16:17], v[166:167], v[174:175]
	v_cvt_pk_bf16_f32 v164, v164, v165
	v_cvt_pk_bf16_f32 v165, v154, v155
	v_cvt_pk_bf16_f32 v168, v168, v169
	s_nop 0
	v_cvt_pk_bf16_f32 v169, v166, v167
	s_nop 0
	v_pk_mul_f32 v[154:155], v[138:139], v[242:243] op_sel_hi:[0,1]
	v_pk_mul_f32 v[152:153], v[138:139], v[246:247] op_sel_hi:[0,1]
	v_pk_mul_f32 v[150:151], v[138:139], v[244:245] op_sel_hi:[0,1]
	v_pk_mul_f32 v[166:167], v[138:139], v[240:241] op_sel_hi:[0,1]
	v_pk_mul_f32 v[170:171], v[4:5], v[152:153]
	v_pk_mul_f32 v[172:173], v[2:3], v[150:151]
	v_pk_mul_f32 v[150:151], v[10:11], v[150:151]
	v_pk_mul_f32 v[152:153], v[12:13], v[152:153]
	v_pk_fma_f32 v[170:171], v[12:13], v[154:155], v[170:171] neg_lo:[0,0,1] neg_hi:[0,0,1]
	v_pk_fma_f32 v[172:173], v[10:11], v[166:167], v[172:173] neg_lo:[0,0,1] neg_hi:[0,0,1]
	v_pk_fma_f32 v[150:151], v[2:3], v[166:167], v[150:151]
	v_cvt_pk_bf16_f32 v166, v172, v173
	v_cvt_pk_bf16_f32 v167, v170, v171
	v_pk_fma_f32 v[152:153], v[4:5], v[154:155], v[152:153]
	v_cvt_pk_bf16_f32 v170, v150, v151
	s_nop 0
	v_cvt_pk_bf16_f32 v171, v152, v153
	global_store_dwordx4 v[148:149], v[164:167], off offset:2048
	global_store_dwordx4 v[148:149], v[168:171], off offset:2112

.LBB0_209:
	v_lshlrev_b32_e32 v138, 4, v161
	s_lshl_b32 s5, s22, 1
	v_lshl_or_b32 v138, s11, 6, v138
	s_add_i32 s4, s4, s5
	v_add_u32_e32 v148, s4, v138
	v_mul_lo_u32 v149, s13, v162
	v_cvt_pk_bf16_f32 v126, v126, v127
	v_cvt_pk_bf16_f32 v127, v128, v129
	v_cvt_pk_bf16_f32 v128, v122, v123
	v_cndmask_b32_e64 v122, 0, 1, s[20:21]
	v_add_u32_e32 v138, v148, v149
	v_cmp_ne_u32_e64 s[4:5], 1, v122
	s_andn2_b64 vcc, exec, s[20:21]
	v_cvt_pk_bf16_f32 v129, v124, v125
	global_store_dwordx4 v138, v[126:129], s[82:83] sc1
	s_cbranch_vccnz .LBB0_211
	v_mul_f32_e32 v123, 0xbfb8aa3b, v114
	v_mul_f32_e32 v124, 0xbfb8aa3b, v119
	v_exp_f32_e32 v123, v123
	v_exp_f32_e32 v125, v124
	v_mul_f32_e32 v127, 0xbfb8aa3b, v116
	v_mul_f32_e32 v128, 0xbfb8aa3b, v121
	v_add_f32_e32 v123, 1.0, v123
	v_mul_f32_e32 v122, 0xbfb8aa3b, v118
	v_rcp_f32_e32 v124, v123
	v_add_f32_e32 v123, 1.0, v125
	v_mul_f32_e32 v125, 0xbfb8aa3b, v115
	v_mul_f32_e32 v126, 0xbfb8aa3b, v120
	v_exp_f32_e32 v127, v127
	v_exp_f32_e32 v129, v128
	v_mul_f32_e32 v128, 0xbfb8aa3b, v117
	v_exp_f32_e32 v122, v122
	v_exp_f32_e32 v125, v125
	v_exp_f32_e32 v126, v126
	v_exp_f32_e32 v150, v128
	v_add_f32_e32 v127, 1.0, v127
	v_add_f32_e32 v122, 1.0, v122
	v_add_f32_e32 v125, 1.0, v125
	v_add_f32_e32 v126, 1.0, v126
	v_rcp_f32_e32 v128, v127
	v_add_f32_e32 v127, 1.0, v129
	v_add_f32_e32 v129, 1.0, v150
	v_rcp_f32_e32 v122, v122
	v_rcp_f32_e32 v123, v123
	v_rcp_f32_e32 v126, v126
	v_rcp_f32_e32 v127, v127
	v_rcp_f32_e32 v129, v129
	v_rcp_f32_e32 v125, v125
	v_pk_mul_f32 v[118:119], v[118:119], v[122:123]
	v_pk_mul_f32 v[120:121], v[120:121], v[126:127]
	v_pk_mul_f32 v[116:117], v[116:117], v[128:129]
	v_pk_mul_f32 v[114:115], v[114:115], v[124:125]
.LBB0_211:
	v_lshl_add_u64 v[122:123], s[82:83], 0, v[138:139]
	s_and_b64 vcc, exec, s[4:5]
	v_cvt_pk_bf16_f32 v118, v118, v119
	v_cvt_pk_bf16_f32 v119, v120, v121
	v_cvt_pk_bf16_f32 v120, v114, v115
	v_cvt_pk_bf16_f32 v121, v116, v117
	global_store_dwordx4 v[122:123], v[118:121], off offset:256 sc1
	s_cbranch_vccnz .LBB0_213
	v_mul_f32_e32 v115, 0xbfb8aa3b, v106
	v_mul_f32_e32 v116, 0xbfb8aa3b, v111
	v_exp_f32_e32 v115, v115
	v_exp_f32_e32 v117, v116
	v_mul_f32_e32 v119, 0xbfb8aa3b, v108
	v_mul_f32_e32 v120, 0xbfb8aa3b, v113
	v_add_f32_e32 v115, 1.0, v115
	v_mul_f32_e32 v114, 0xbfb8aa3b, v110
	v_rcp_f32_e32 v116, v115
	v_add_f32_e32 v115, 1.0, v117
	v_mul_f32_e32 v117, 0xbfb8aa3b, v107
	v_mul_f32_e32 v118, 0xbfb8aa3b, v112
	v_exp_f32_e32 v119, v119
	v_exp_f32_e32 v121, v120
	v_mul_f32_e32 v120, 0xbfb8aa3b, v109
	v_exp_f32_e32 v114, v114
	v_exp_f32_e32 v117, v117
	v_exp_f32_e32 v118, v118
	v_exp_f32_e32 v122, v120
	v_add_f32_e32 v119, 1.0, v119
	v_add_f32_e32 v114, 1.0, v114
	v_add_f32_e32 v117, 1.0, v117
	v_add_f32_e32 v118, 1.0, v118
	v_rcp_f32_e32 v120, v119
	v_add_f32_e32 v119, 1.0, v121
	v_add_f32_e32 v121, 1.0, v122
	v_rcp_f32_e32 v114, v114
	v_rcp_f32_e32 v115, v115
	v_rcp_f32_e32 v118, v118
	v_rcp_f32_e32 v119, v119
	v_rcp_f32_e32 v121, v121
	v_rcp_f32_e32 v117, v117
	v_pk_mul_f32 v[110:111], v[110:111], v[114:115]
	v_pk_mul_f32 v[112:113], v[112:113], v[118:119]
	v_pk_mul_f32 v[108:109], v[108:109], v[120:121]
	v_pk_mul_f32 v[106:107], v[106:107], v[116:117]
.LBB0_213:
	s_lshl_b32 s11, s13, 4
	v_add_u32_e32 v114, s11, v149
	v_add_u32_e32 v138, v148, v114
	s_and_b64 vcc, exec, s[4:5]
	v_cvt_pk_bf16_f32 v110, v110, v111
	v_cvt_pk_bf16_f32 v111, v112, v113
	v_cvt_pk_bf16_f32 v112, v106, v107
	v_cvt_pk_bf16_f32 v113, v108, v109
	global_store_dwordx4 v138, v[110:113], s[82:83] sc1
	s_cbranch_vccnz .LBB0_215
	v_mul_f32_e32 v107, 0xbfb8aa3b, v98
	v_mul_f32_e32 v108, 0xbfb8aa3b, v103
	v_exp_f32_e32 v107, v107
	v_exp_f32_e32 v109, v108
	v_mul_f32_e32 v111, 0xbfb8aa3b, v100
	v_mul_f32_e32 v112, 0xbfb8aa3b, v105
	v_add_f32_e32 v107, 1.0, v107
	v_mul_f32_e32 v106, 0xbfb8aa3b, v102
	v_rcp_f32_e32 v108, v107
	v_add_f32_e32 v107, 1.0, v109
	v_mul_f32_e32 v109, 0xbfb8aa3b, v99
	v_mul_f32_e32 v110, 0xbfb8aa3b, v104
	v_exp_f32_e32 v111, v111
	v_exp_f32_e32 v113, v112
	v_mul_f32_e32 v112, 0xbfb8aa3b, v101
	v_exp_f32_e32 v106, v106
	v_exp_f32_e32 v109, v109
	v_exp_f32_e32 v110, v110
	v_exp_f32_e32 v115, v112
	v_add_f32_e32 v111, 1.0, v111
	v_add_f32_e32 v106, 1.0, v106
	v_add_f32_e32 v109, 1.0, v109
	v_add_f32_e32 v110, 1.0, v110
	v_rcp_f32_e32 v112, v111
	v_add_f32_e32 v111, 1.0, v113
	v_add_f32_e32 v113, 1.0, v115
	v_rcp_f32_e32 v106, v106
	v_rcp_f32_e32 v107, v107
	v_rcp_f32_e32 v110, v110
	v_rcp_f32_e32 v111, v111
	v_rcp_f32_e32 v113, v113
	v_rcp_f32_e32 v109, v109
	v_pk_mul_f32 v[102:103], v[102:103], v[106:107]
	v_pk_mul_f32 v[104:105], v[104:105], v[110:111]
	v_pk_mul_f32 v[100:101], v[100:101], v[112:113]
	v_pk_mul_f32 v[98:99], v[98:99], v[108:109]
.LBB0_215:
	v_lshl_add_u64 v[106:107], s[82:83], 0, v[138:139]
	s_and_b64 vcc, exec, s[4:5]
	v_cvt_pk_bf16_f32 v102, v102, v103
	v_cvt_pk_bf16_f32 v103, v104, v105
	v_cvt_pk_bf16_f32 v104, v98, v99
	v_cvt_pk_bf16_f32 v105, v100, v101
	global_store_dwordx4 v[106:107], v[102:105], off offset:256 sc1
	s_cbranch_vccnz .LBB0_217
	v_mul_f32_e32 v99, 0xbfb8aa3b, v90
	v_mul_f32_e32 v100, 0xbfb8aa3b, v95
	v_exp_f32_e32 v99, v99
	v_exp_f32_e32 v101, v100
	v_mul_f32_e32 v103, 0xbfb8aa3b, v92
	v_mul_f32_e32 v104, 0xbfb8aa3b, v97
	v_add_f32_e32 v99, 1.0, v99
	v_mul_f32_e32 v98, 0xbfb8aa3b, v94
	v_rcp_f32_e32 v100, v99
	v_add_f32_e32 v99, 1.0, v101
	v_mul_f32_e32 v101, 0xbfb8aa3b, v91
	v_mul_f32_e32 v102, 0xbfb8aa3b, v96
	v_exp_f32_e32 v103, v103
	v_exp_f32_e32 v105, v104
	v_mul_f32_e32 v104, 0xbfb8aa3b, v93
	v_exp_f32_e32 v98, v98
	v_exp_f32_e32 v101, v101
	v_exp_f32_e32 v102, v102
	v_exp_f32_e32 v106, v104
	v_add_f32_e32 v103, 1.0, v103
	v_add_f32_e32 v98, 1.0, v98
	v_add_f32_e32 v101, 1.0, v101
	v_add_f32_e32 v102, 1.0, v102
	v_rcp_f32_e32 v104, v103
	v_add_f32_e32 v103, 1.0, v105
	v_add_f32_e32 v105, 1.0, v106
	v_rcp_f32_e32 v98, v98
	v_rcp_f32_e32 v99, v99
	v_rcp_f32_e32 v102, v102
	v_rcp_f32_e32 v103, v103
	v_rcp_f32_e32 v105, v105
	v_rcp_f32_e32 v101, v101
	v_pk_mul_f32 v[94:95], v[94:95], v[98:99]
	v_pk_mul_f32 v[96:97], v[96:97], v[102:103]
	v_pk_mul_f32 v[92:93], v[92:93], v[104:105]
	v_pk_mul_f32 v[90:91], v[90:91], v[100:101]
.LBB0_217:
	v_add_u32_e32 v98, s11, v114
	v_add_u32_e32 v138, v148, v98
	s_and_b64 vcc, exec, s[4:5]
	v_cvt_pk_bf16_f32 v94, v94, v95
	v_cvt_pk_bf16_f32 v95, v96, v97
	v_cvt_pk_bf16_f32 v96, v90, v91
	v_cvt_pk_bf16_f32 v97, v92, v93
	global_store_dwordx4 v138, v[94:97], s[82:83] sc1
	s_cbranch_vccnz .LBB0_219
	v_mul_f32_e32 v91, 0xbfb8aa3b, v82
	v_mul_f32_e32 v92, 0xbfb8aa3b, v87
	v_exp_f32_e32 v91, v91
	v_exp_f32_e32 v93, v92
	v_mul_f32_e32 v95, 0xbfb8aa3b, v84
	v_mul_f32_e32 v96, 0xbfb8aa3b, v89
	v_add_f32_e32 v91, 1.0, v91
	v_mul_f32_e32 v90, 0xbfb8aa3b, v86
	v_rcp_f32_e32 v92, v91
	v_add_f32_e32 v91, 1.0, v93
	v_mul_f32_e32 v93, 0xbfb8aa3b, v83
	v_mul_f32_e32 v94, 0xbfb8aa3b, v88
	v_exp_f32_e32 v95, v95
	v_exp_f32_e32 v97, v96
	v_mul_f32_e32 v96, 0xbfb8aa3b, v85
	v_exp_f32_e32 v90, v90
	v_exp_f32_e32 v93, v93
	v_exp_f32_e32 v94, v94
	v_exp_f32_e32 v99, v96
	v_add_f32_e32 v95, 1.0, v95
	v_add_f32_e32 v90, 1.0, v90
	v_add_f32_e32 v93, 1.0, v93
	v_add_f32_e32 v94, 1.0, v94
	v_rcp_f32_e32 v96, v95
	v_add_f32_e32 v95, 1.0, v97
	v_add_f32_e32 v97, 1.0, v99
	v_rcp_f32_e32 v90, v90
	v_rcp_f32_e32 v91, v91
	v_rcp_f32_e32 v94, v94
	v_rcp_f32_e32 v95, v95
	v_rcp_f32_e32 v97, v97
	v_rcp_f32_e32 v93, v93
	v_pk_mul_f32 v[86:87], v[86:87], v[90:91]
	v_pk_mul_f32 v[88:89], v[88:89], v[94:95]
	v_pk_mul_f32 v[84:85], v[84:85], v[96:97]
	v_pk_mul_f32 v[82:83], v[82:83], v[92:93]
.LBB0_219:
	v_lshl_add_u64 v[90:91], s[82:83], 0, v[138:139]
	s_and_b64 vcc, exec, s[4:5]
	v_cvt_pk_bf16_f32 v86, v86, v87
	v_cvt_pk_bf16_f32 v87, v88, v89
	v_cvt_pk_bf16_f32 v88, v82, v83
	v_cvt_pk_bf16_f32 v89, v84, v85
	global_store_dwordx4 v[90:91], v[86:89], off offset:256 sc1
	s_cbranch_vccnz .LBB0_221
	v_mul_f32_e32 v83, 0xbfb8aa3b, v74
	v_mul_f32_e32 v84, 0xbfb8aa3b, v79
	v_exp_f32_e32 v83, v83
	v_exp_f32_e32 v85, v84
	v_mul_f32_e32 v87, 0xbfb8aa3b, v76
	v_mul_f32_e32 v88, 0xbfb8aa3b, v81
	v_add_f32_e32 v83, 1.0, v83
	v_mul_f32_e32 v82, 0xbfb8aa3b, v78
	v_rcp_f32_e32 v84, v83
	v_add_f32_e32 v83, 1.0, v85
	v_mul_f32_e32 v85, 0xbfb8aa3b, v75
	v_mul_f32_e32 v86, 0xbfb8aa3b, v80
	v_exp_f32_e32 v87, v87
	v_exp_f32_e32 v89, v88
	v_mul_f32_e32 v88, 0xbfb8aa3b, v77
	v_exp_f32_e32 v82, v82
	v_exp_f32_e32 v85, v85
	v_exp_f32_e32 v86, v86
	v_exp_f32_e32 v90, v88
	v_add_f32_e32 v87, 1.0, v87
	v_add_f32_e32 v82, 1.0, v82
	v_add_f32_e32 v85, 1.0, v85
	v_add_f32_e32 v86, 1.0, v86
	v_rcp_f32_e32 v88, v87
	v_add_f32_e32 v87, 1.0, v89
	v_add_f32_e32 v89, 1.0, v90
	v_rcp_f32_e32 v82, v82
	v_rcp_f32_e32 v83, v83
	v_rcp_f32_e32 v86, v86
	v_rcp_f32_e32 v87, v87
	v_rcp_f32_e32 v89, v89
	v_rcp_f32_e32 v85, v85
	v_pk_mul_f32 v[78:79], v[78:79], v[82:83]
	v_pk_mul_f32 v[80:81], v[80:81], v[86:87]
	v_pk_mul_f32 v[76:77], v[76:77], v[88:89]
	v_pk_mul_f32 v[74:75], v[74:75], v[84:85]
.LBB0_221:
	v_add_u32_e32 v82, s11, v98
	v_add_u32_e32 v138, v148, v82
	s_and_b64 vcc, exec, s[4:5]
	v_cvt_pk_bf16_f32 v78, v78, v79
	v_cvt_pk_bf16_f32 v79, v80, v81
	v_cvt_pk_bf16_f32 v80, v74, v75
	v_cvt_pk_bf16_f32 v81, v76, v77
	global_store_dwordx4 v138, v[78:81], s[82:83] sc1
	s_cbranch_vccnz .LBB0_223
	v_mul_f32_e32 v75, 0xbfb8aa3b, v66
	v_mul_f32_e32 v76, 0xbfb8aa3b, v71
	v_exp_f32_e32 v75, v75
	v_exp_f32_e32 v77, v76
	v_mul_f32_e32 v79, 0xbfb8aa3b, v68
	v_mul_f32_e32 v80, 0xbfb8aa3b, v73
	v_add_f32_e32 v75, 1.0, v75
	v_mul_f32_e32 v74, 0xbfb8aa3b, v70
	v_rcp_f32_e32 v76, v75
	v_add_f32_e32 v75, 1.0, v77
	v_mul_f32_e32 v77, 0xbfb8aa3b, v67
	v_mul_f32_e32 v78, 0xbfb8aa3b, v72
	v_exp_f32_e32 v79, v79
	v_exp_f32_e32 v81, v80
	v_mul_f32_e32 v80, 0xbfb8aa3b, v69
	v_exp_f32_e32 v74, v74
	v_exp_f32_e32 v77, v77
	v_exp_f32_e32 v78, v78
	v_exp_f32_e32 v83, v80
	v_add_f32_e32 v79, 1.0, v79
	v_add_f32_e32 v74, 1.0, v74
	v_add_f32_e32 v77, 1.0, v77
	v_add_f32_e32 v78, 1.0, v78
	v_rcp_f32_e32 v80, v79
	v_add_f32_e32 v79, 1.0, v81
	v_add_f32_e32 v81, 1.0, v83
	v_rcp_f32_e32 v74, v74
	v_rcp_f32_e32 v75, v75
	v_rcp_f32_e32 v78, v78
	v_rcp_f32_e32 v79, v79
	v_rcp_f32_e32 v81, v81
	v_rcp_f32_e32 v77, v77
	v_pk_mul_f32 v[70:71], v[70:71], v[74:75]
	v_pk_mul_f32 v[72:73], v[72:73], v[78:79]
	v_pk_mul_f32 v[68:69], v[68:69], v[80:81]
	v_pk_mul_f32 v[66:67], v[66:67], v[76:77]
.LBB0_223:
	v_lshl_add_u64 v[74:75], s[82:83], 0, v[138:139]
	s_and_b64 vcc, exec, s[4:5]
	v_cvt_pk_bf16_f32 v70, v70, v71
	v_cvt_pk_bf16_f32 v71, v72, v73
	v_cvt_pk_bf16_f32 v72, v66, v67
	v_cvt_pk_bf16_f32 v73, v68, v69
	global_store_dwordx4 v[74:75], v[70:73], off offset:256 sc1
	s_cbranch_vccnz .LBB0_225
	v_mul_f32_e32 v67, 0xbfb8aa3b, v58
	v_mul_f32_e32 v68, 0xbfb8aa3b, v63
	v_exp_f32_e32 v67, v67
	v_exp_f32_e32 v69, v68
	v_mul_f32_e32 v71, 0xbfb8aa3b, v60
	v_mul_f32_e32 v72, 0xbfb8aa3b, v65
	v_add_f32_e32 v67, 1.0, v67
	v_mul_f32_e32 v66, 0xbfb8aa3b, v62
	v_rcp_f32_e32 v68, v67
	v_add_f32_e32 v67, 1.0, v69
	v_mul_f32_e32 v69, 0xbfb8aa3b, v59
	v_mul_f32_e32 v70, 0xbfb8aa3b, v64
	v_exp_f32_e32 v71, v71
	v_exp_f32_e32 v73, v72
	v_mul_f32_e32 v72, 0xbfb8aa3b, v61
	v_exp_f32_e32 v66, v66
	v_exp_f32_e32 v69, v69
	v_exp_f32_e32 v70, v70
	v_exp_f32_e32 v74, v72
	v_add_f32_e32 v71, 1.0, v71
	v_add_f32_e32 v66, 1.0, v66
	v_add_f32_e32 v69, 1.0, v69
	v_add_f32_e32 v70, 1.0, v70
	v_rcp_f32_e32 v72, v71
	v_add_f32_e32 v71, 1.0, v73
	v_add_f32_e32 v73, 1.0, v74
	v_rcp_f32_e32 v66, v66
	v_rcp_f32_e32 v67, v67
	v_rcp_f32_e32 v70, v70
	v_rcp_f32_e32 v71, v71
	v_rcp_f32_e32 v73, v73
	v_rcp_f32_e32 v69, v69
	v_pk_mul_f32 v[62:63], v[62:63], v[66:67]
	v_pk_mul_f32 v[64:65], v[64:65], v[70:71]
	v_pk_mul_f32 v[60:61], v[60:61], v[72:73]
	v_pk_mul_f32 v[58:59], v[58:59], v[68:69]
.LBB0_225:
	s_mulk_i32 s13, 0x50
	v_add_u32_e32 v66, s13, v82
	v_add_u32_e32 v138, v148, v66
	s_and_b64 vcc, exec, s[4:5]
	v_cvt_pk_bf16_f32 v62, v62, v63
	v_cvt_pk_bf16_f32 v63, v64, v65
	v_cvt_pk_bf16_f32 v64, v58, v59
	v_cvt_pk_bf16_f32 v65, v60, v61
	global_store_dwordx4 v138, v[62:65], s[82:83] sc1
	s_cbranch_vccnz .LBB0_227
	v_mul_f32_e32 v59, 0xbfb8aa3b, v50
	v_mul_f32_e32 v60, 0xbfb8aa3b, v55
	v_exp_f32_e32 v59, v59
	v_exp_f32_e32 v61, v60
	v_mul_f32_e32 v63, 0xbfb8aa3b, v52
	v_mul_f32_e32 v64, 0xbfb8aa3b, v57
	v_add_f32_e32 v59, 1.0, v59
	v_mul_f32_e32 v58, 0xbfb8aa3b, v54
	v_rcp_f32_e32 v60, v59
	v_add_f32_e32 v59, 1.0, v61
	v_mul_f32_e32 v61, 0xbfb8aa3b, v51
	v_mul_f32_e32 v62, 0xbfb8aa3b, v56
	v_exp_f32_e32 v63, v63
	v_exp_f32_e32 v65, v64
	v_mul_f32_e32 v64, 0xbfb8aa3b, v53
	v_exp_f32_e32 v58, v58
	v_exp_f32_e32 v61, v61
	v_exp_f32_e32 v62, v62
	v_exp_f32_e32 v67, v64
	v_add_f32_e32 v63, 1.0, v63
	v_add_f32_e32 v58, 1.0, v58
	v_add_f32_e32 v61, 1.0, v61
	v_add_f32_e32 v62, 1.0, v62
	v_rcp_f32_e32 v64, v63
	v_add_f32_e32 v63, 1.0, v65
	v_add_f32_e32 v65, 1.0, v67
	v_rcp_f32_e32 v58, v58
	v_rcp_f32_e32 v59, v59
	v_rcp_f32_e32 v62, v62
	v_rcp_f32_e32 v63, v63
	v_rcp_f32_e32 v65, v65
	v_rcp_f32_e32 v61, v61
	v_pk_mul_f32 v[54:55], v[54:55], v[58:59]
	v_pk_mul_f32 v[56:57], v[56:57], v[62:63]
	v_pk_mul_f32 v[52:53], v[52:53], v[64:65]
	v_pk_mul_f32 v[50:51], v[50:51], v[60:61]
.LBB0_227:
	v_lshl_add_u64 v[58:59], s[82:83], 0, v[138:139]
	s_and_b64 vcc, exec, s[4:5]
	v_cvt_pk_bf16_f32 v54, v54, v55
	v_cvt_pk_bf16_f32 v55, v56, v57
	v_cvt_pk_bf16_f32 v56, v50, v51
	v_cvt_pk_bf16_f32 v57, v52, v53
	global_store_dwordx4 v[58:59], v[54:57], off offset:256 sc1
	s_cbranch_vccnz .LBB0_229
	v_mul_f32_e32 v51, 0xbfb8aa3b, v42
	v_mul_f32_e32 v52, 0xbfb8aa3b, v47
	v_exp_f32_e32 v51, v51
	v_exp_f32_e32 v53, v52
	v_mul_f32_e32 v55, 0xbfb8aa3b, v44
	v_mul_f32_e32 v56, 0xbfb8aa3b, v49
	v_add_f32_e32 v51, 1.0, v51
	v_mul_f32_e32 v50, 0xbfb8aa3b, v46
	v_rcp_f32_e32 v52, v51
	v_add_f32_e32 v51, 1.0, v53
	v_mul_f32_e32 v53, 0xbfb8aa3b, v43
	v_mul_f32_e32 v54, 0xbfb8aa3b, v48
	v_exp_f32_e32 v55, v55
	v_exp_f32_e32 v57, v56
	v_mul_f32_e32 v56, 0xbfb8aa3b, v45
	v_exp_f32_e32 v50, v50
	v_exp_f32_e32 v53, v53
	v_exp_f32_e32 v54, v54
	v_exp_f32_e32 v58, v56
	v_add_f32_e32 v55, 1.0, v55
	v_add_f32_e32 v50, 1.0, v50
	v_add_f32_e32 v53, 1.0, v53
	v_add_f32_e32 v54, 1.0, v54
	v_rcp_f32_e32 v56, v55
	v_add_f32_e32 v55, 1.0, v57
	v_add_f32_e32 v57, 1.0, v58
	v_rcp_f32_e32 v50, v50
	v_rcp_f32_e32 v51, v51
	v_rcp_f32_e32 v54, v54
	v_rcp_f32_e32 v55, v55
	v_rcp_f32_e32 v57, v57
	v_rcp_f32_e32 v53, v53
	v_pk_mul_f32 v[46:47], v[46:47], v[50:51]
	v_pk_mul_f32 v[48:49], v[48:49], v[54:55]
	v_pk_mul_f32 v[44:45], v[44:45], v[56:57]
	v_pk_mul_f32 v[42:43], v[42:43], v[52:53]
.LBB0_229:
	v_add_u32_e32 v50, s11, v66
	v_add_u32_e32 v138, v148, v50
	s_and_b64 vcc, exec, s[4:5]
	v_cvt_pk_bf16_f32 v46, v46, v47
	v_cvt_pk_bf16_f32 v47, v48, v49
	v_cvt_pk_bf16_f32 v48, v42, v43
	v_cvt_pk_bf16_f32 v49, v44, v45
	global_store_dwordx4 v138, v[46:49], s[82:83] sc1
	s_cbranch_vccnz .LBB0_231
	v_mul_f32_e32 v43, 0xbfb8aa3b, v34
	v_mul_f32_e32 v44, 0xbfb8aa3b, v39
	v_exp_f32_e32 v43, v43
	v_exp_f32_e32 v45, v44
	v_mul_f32_e32 v47, 0xbfb8aa3b, v36
	v_mul_f32_e32 v48, 0xbfb8aa3b, v41
	v_add_f32_e32 v43, 1.0, v43
	v_mul_f32_e32 v42, 0xbfb8aa3b, v38
	v_rcp_f32_e32 v44, v43
	v_add_f32_e32 v43, 1.0, v45
	v_mul_f32_e32 v45, 0xbfb8aa3b, v35
	v_mul_f32_e32 v46, 0xbfb8aa3b, v40
	v_exp_f32_e32 v47, v47
	v_exp_f32_e32 v49, v48
	v_mul_f32_e32 v48, 0xbfb8aa3b, v37
	v_exp_f32_e32 v42, v42
	v_exp_f32_e32 v45, v45
	v_exp_f32_e32 v46, v46
	v_exp_f32_e32 v51, v48
	v_add_f32_e32 v47, 1.0, v47
	v_add_f32_e32 v42, 1.0, v42
	v_add_f32_e32 v45, 1.0, v45
	v_add_f32_e32 v46, 1.0, v46
	v_rcp_f32_e32 v48, v47
	v_add_f32_e32 v47, 1.0, v49
	v_add_f32_e32 v49, 1.0, v51
	v_rcp_f32_e32 v42, v42
	v_rcp_f32_e32 v43, v43
	v_rcp_f32_e32 v46, v46
	v_rcp_f32_e32 v47, v47
	v_rcp_f32_e32 v49, v49
	v_rcp_f32_e32 v45, v45
	v_pk_mul_f32 v[38:39], v[38:39], v[42:43]
	v_pk_mul_f32 v[40:41], v[40:41], v[46:47]
	v_pk_mul_f32 v[36:37], v[36:37], v[48:49]
	v_pk_mul_f32 v[34:35], v[34:35], v[44:45]
.LBB0_231:
	v_lshl_add_u64 v[42:43], s[82:83], 0, v[138:139]
	s_and_b64 vcc, exec, s[4:5]
	v_cvt_pk_bf16_f32 v38, v38, v39
	v_cvt_pk_bf16_f32 v39, v40, v41
	v_cvt_pk_bf16_f32 v40, v34, v35
	v_cvt_pk_bf16_f32 v41, v36, v37
	global_store_dwordx4 v[42:43], v[38:41], off offset:256 sc1
	s_cbranch_vccnz .LBB0_233
	v_mul_f32_e32 v35, 0xbfb8aa3b, v26
	v_mul_f32_e32 v36, 0xbfb8aa3b, v31
	v_exp_f32_e32 v35, v35
	v_exp_f32_e32 v37, v36
	v_mul_f32_e32 v39, 0xbfb8aa3b, v28
	v_mul_f32_e32 v40, 0xbfb8aa3b, v33
	v_add_f32_e32 v35, 1.0, v35
	v_mul_f32_e32 v34, 0xbfb8aa3b, v30
	v_rcp_f32_e32 v36, v35
	v_add_f32_e32 v35, 1.0, v37
	v_mul_f32_e32 v37, 0xbfb8aa3b, v27
	v_mul_f32_e32 v38, 0xbfb8aa3b, v32
	v_exp_f32_e32 v39, v39
	v_exp_f32_e32 v41, v40
	v_mul_f32_e32 v40, 0xbfb8aa3b, v29
	v_exp_f32_e32 v34, v34
	v_exp_f32_e32 v37, v37
	v_exp_f32_e32 v38, v38
	v_exp_f32_e32 v42, v40
	v_add_f32_e32 v39, 1.0, v39
	v_add_f32_e32 v34, 1.0, v34
	v_add_f32_e32 v37, 1.0, v37
	v_add_f32_e32 v38, 1.0, v38
	v_rcp_f32_e32 v40, v39
	v_add_f32_e32 v39, 1.0, v41
	v_add_f32_e32 v41, 1.0, v42
	v_rcp_f32_e32 v34, v34
	v_rcp_f32_e32 v35, v35
	v_rcp_f32_e32 v38, v38
	v_rcp_f32_e32 v39, v39
	v_rcp_f32_e32 v41, v41
	v_rcp_f32_e32 v37, v37
	v_pk_mul_f32 v[30:31], v[30:31], v[34:35]
	v_pk_mul_f32 v[32:33], v[32:33], v[38:39]
	v_pk_mul_f32 v[28:29], v[28:29], v[40:41]
	v_pk_mul_f32 v[26:27], v[26:27], v[36:37]
.LBB0_233:
	v_add_u32_e32 v34, s11, v50
	v_add_u32_e32 v138, v148, v34
	s_and_b64 vcc, exec, s[4:5]
	v_cvt_pk_bf16_f32 v30, v30, v31
	v_cvt_pk_bf16_f32 v31, v32, v33
	v_cvt_pk_bf16_f32 v32, v26, v27
	v_cvt_pk_bf16_f32 v33, v28, v29
	global_store_dwordx4 v138, v[30:33], s[82:83] sc1
	s_cbranch_vccnz .LBB0_235
	v_mul_f32_e32 v27, 0xbfb8aa3b, v18
	v_mul_f32_e32 v28, 0xbfb8aa3b, v23
	v_exp_f32_e32 v27, v27
	v_exp_f32_e32 v29, v28
	v_mul_f32_e32 v31, 0xbfb8aa3b, v20
	v_mul_f32_e32 v32, 0xbfb8aa3b, v25
	v_add_f32_e32 v27, 1.0, v27
	v_mul_f32_e32 v26, 0xbfb8aa3b, v22
	v_rcp_f32_e32 v28, v27
	v_add_f32_e32 v27, 1.0, v29
	v_mul_f32_e32 v29, 0xbfb8aa3b, v19
	v_mul_f32_e32 v30, 0xbfb8aa3b, v24
	v_exp_f32_e32 v31, v31
	v_exp_f32_e32 v33, v32
	v_mul_f32_e32 v32, 0xbfb8aa3b, v21
	v_exp_f32_e32 v26, v26
	v_exp_f32_e32 v29, v29
	v_exp_f32_e32 v30, v30
	v_exp_f32_e32 v35, v32
	v_add_f32_e32 v31, 1.0, v31
	v_add_f32_e32 v26, 1.0, v26
	v_add_f32_e32 v29, 1.0, v29
	v_add_f32_e32 v30, 1.0, v30
	v_rcp_f32_e32 v32, v31
	v_add_f32_e32 v31, 1.0, v33
	v_add_f32_e32 v33, 1.0, v35
	v_rcp_f32_e32 v26, v26
	v_rcp_f32_e32 v27, v27
	v_rcp_f32_e32 v30, v30
	v_rcp_f32_e32 v31, v31
	v_rcp_f32_e32 v33, v33
	v_rcp_f32_e32 v29, v29
	v_pk_mul_f32 v[22:23], v[22:23], v[26:27]
	v_pk_mul_f32 v[24:25], v[24:25], v[30:31]
	v_pk_mul_f32 v[20:21], v[20:21], v[32:33]
	v_pk_mul_f32 v[18:19], v[18:19], v[28:29]
.LBB0_235:
	v_lshl_add_u64 v[26:27], s[82:83], 0, v[138:139]
	s_and_b64 vcc, exec, s[4:5]
	v_cvt_pk_bf16_f32 v22, v22, v23
	v_cvt_pk_bf16_f32 v23, v24, v25
	v_cvt_pk_bf16_f32 v24, v18, v19
	v_cvt_pk_bf16_f32 v25, v20, v21
	global_store_dwordx4 v[26:27], v[22:25], off offset:256 sc1
	s_cbranch_vccnz .LBB0_237
	v_mul_f32_e32 v19, 0xbfb8aa3b, v10
	v_mul_f32_e32 v20, 0xbfb8aa3b, v15
	v_exp_f32_e32 v19, v19
	v_exp_f32_e32 v21, v20
	v_mul_f32_e32 v23, 0xbfb8aa3b, v12
	v_mul_f32_e32 v24, 0xbfb8aa3b, v17
	v_add_f32_e32 v19, 1.0, v19
	v_mul_f32_e32 v18, 0xbfb8aa3b, v14
	v_rcp_f32_e32 v20, v19
	v_add_f32_e32 v19, 1.0, v21
	v_mul_f32_e32 v21, 0xbfb8aa3b, v11
	v_mul_f32_e32 v22, 0xbfb8aa3b, v16
	v_exp_f32_e32 v23, v23
	v_exp_f32_e32 v25, v24
	v_mul_f32_e32 v24, 0xbfb8aa3b, v13
	v_exp_f32_e32 v18, v18
	v_exp_f32_e32 v21, v21
	v_exp_f32_e32 v22, v22
	v_exp_f32_e32 v26, v24
	v_add_f32_e32 v23, 1.0, v23
	v_add_f32_e32 v18, 1.0, v18
	v_add_f32_e32 v21, 1.0, v21
	v_add_f32_e32 v22, 1.0, v22
	v_rcp_f32_e32 v24, v23
	v_add_f32_e32 v23, 1.0, v25
	v_add_f32_e32 v25, 1.0, v26
	v_rcp_f32_e32 v18, v18
	v_rcp_f32_e32 v19, v19
	v_rcp_f32_e32 v22, v22
	v_rcp_f32_e32 v23, v23
	v_rcp_f32_e32 v25, v25
	v_rcp_f32_e32 v21, v21
	v_pk_mul_f32 v[14:15], v[14:15], v[18:19]
	v_pk_mul_f32 v[16:17], v[16:17], v[22:23]
	v_pk_mul_f32 v[12:13], v[12:13], v[24:25]
	v_pk_mul_f32 v[10:11], v[10:11], v[20:21]
.LBB0_237:
	v_add3_u32 v138, v34, s11, v148
	s_and_b64 vcc, exec, s[4:5]
	v_cvt_pk_bf16_f32 v14, v14, v15
	v_cvt_pk_bf16_f32 v15, v16, v17
	v_cvt_pk_bf16_f32 v16, v10, v11
	v_cvt_pk_bf16_f32 v17, v12, v13
	global_store_dwordx4 v138, v[14:17], s[82:83] sc1
	s_cbranch_vccnz .LBB0_239
	v_mul_f32_e32 v11, 0xbfb8aa3b, v2
	v_mul_f32_e32 v12, 0xbfb8aa3b, v7
	v_exp_f32_e32 v11, v11
	v_exp_f32_e32 v13, v12
	v_mul_f32_e32 v15, 0xbfb8aa3b, v4
	v_mul_f32_e32 v16, 0xbfb8aa3b, v9
	v_add_f32_e32 v11, 1.0, v11
	v_mul_f32_e32 v10, 0xbfb8aa3b, v6
	v_rcp_f32_e32 v12, v11
	v_add_f32_e32 v11, 1.0, v13
	v_mul_f32_e32 v13, 0xbfb8aa3b, v3
	v_mul_f32_e32 v14, 0xbfb8aa3b, v8
	v_exp_f32_e32 v15, v15
	v_exp_f32_e32 v17, v16
	v_mul_f32_e32 v16, 0xbfb8aa3b, v5
	v_exp_f32_e32 v10, v10
	v_exp_f32_e32 v13, v13
	v_exp_f32_e32 v14, v14
	v_exp_f32_e32 v18, v16
	v_add_f32_e32 v15, 1.0, v15
	v_add_f32_e32 v10, 1.0, v10
	v_add_f32_e32 v13, 1.0, v13
	v_add_f32_e32 v14, 1.0, v14
	v_rcp_f32_e32 v16, v15
	v_add_f32_e32 v15, 1.0, v17
	v_add_f32_e32 v17, 1.0, v18
	v_rcp_f32_e32 v10, v10
	v_rcp_f32_e32 v11, v11
	v_rcp_f32_e32 v14, v14
	v_rcp_f32_e32 v15, v15
	v_rcp_f32_e32 v17, v17
	v_rcp_f32_e32 v13, v13
	v_pk_mul_f32 v[6:7], v[6:7], v[10:11]
	v_pk_mul_f32 v[8:9], v[8:9], v[14:15]
	v_pk_mul_f32 v[4:5], v[4:5], v[16:17]
	v_pk_mul_f32 v[2:3], v[2:3], v[12:13]
.LBB0_239:
	v_lshl_add_u64 v[10:11], s[82:83], 0, v[138:139]
	v_cvt_pk_bf16_f32 v6, v6, v7
	v_cvt_pk_bf16_f32 v7, v8, v9
	v_cvt_pk_bf16_f32 v8, v2, v3
	v_cvt_pk_bf16_f32 v9, v4, v5
	global_store_dwordx4 v[10:11], v[6:9], off offset:256 sc1
	s_andn2_b64 vcc, exec, s[2:3]
	s_mov_b64 s[2:3], -1
	s_cbranch_vccnz .LBB0_182

.LBB0_261:
	s_or_b64 exec, exec, s[6:7]
	v_cvt_f32_u32_e32 v6, v4
	s_waitcnt vmcnt(0)
	v_readfirstlane_b32 s4, v5
	v_sub_u32_e32 v5, 0, v4
	v_rcp_iflag_f32_e32 v6, v6
	v_add_u32_e32 v7, s4, v3
	v_mul_f32_e32 v6, 0x4f7ffffe, v6
	v_cvt_u32_f32_e32 v6, v6
	v_mul_lo_u32 v3, v5, v6
	v_mul_hi_u32 v3, v6, v3
	v_add_u32_e32 v3, v6, v3
	v_mul_hi_u32 v3, v7, v3
	v_mul_lo_u32 v5, v3, v4
	v_sub_u32_e32 v5, v7, v5
	v_add_u32_e32 v6, 1, v3
	v_cmp_ge_u32_e32 vcc, v5, v4
	s_nop 1
	v_cndmask_b32_e32 v3, v3, v6, vcc
	v_sub_u32_e32 v6, v5, v4
	v_cndmask_b32_e32 v5, v5, v6, vcc
	v_add_u32_e32 v6, 1, v3
	v_cmp_ge_u32_e32 vcc, v5, v4
	v_add_u32_e32 v5, 1, v7
	s_nop 0
	v_cndmask_b32_e32 v3, v3, v6, vcc
	v_mul_lo_u32 v6, v4, v3
	v_add_u32_e32 v4, v6, v4
	v_cmp_ne_u32_e32 vcc, v5, v4
	s_and_saveexec_b64 s[4:5], vcc
	s_xor_b64 s[4:5], exec, s[4:5]
	s_cbranch_execz .LBB0_275
	s_waitcnt lgkmcnt(0)
	v_mov_b32_e32 v2, 0x7000
	buffer_inv sc1
	s_branch .Lsplit3_nl
	global_load_dword v2, v2, s[82:83] offset:1280 sc1
	s_add_u32 s10, s82, 0x7500
	s_addc_u32 s11, s83, 0
	s_waitcnt vmcnt(0)
	v_cmp_eq_u32_e32 vcc, v2, v3
	s_and_saveexec_b64 s[6:7], vcc
	s_cbranch_execz .LBB0_274
	s_add_u32 s8, s82, 0x4200
	s_addc_u32 s9, s83, 0
	s_mov_b32 s22, 1
	s_mov_b64 s[12:13], 0
	v_mov_b32_e32 v2, 0
	s_branch .LBB0_265

.LBB0_278:
	s_or_b64 exec, exec, s[6:7]
	v_cvt_f32_u32_e32 v5, v2
	s_waitcnt vmcnt(0)
	v_readfirstlane_b32 s4, v4
	s_add_u32 s6, s82, 0x7500
	s_addc_u32 s7, s83, 0
	v_rcp_iflag_f32_e32 v5, v5
	v_add_u32_e32 v3, s4, v3
	v_add_u32_e32 v6, 1, v3
	s_mov_b64 s[8:9], -1
	v_mul_f32_e32 v4, 0x4f7ffffe, v5
	v_cvt_u32_f32_e32 v4, v4
	v_sub_u32_e32 v5, 0, v2
	v_mul_lo_u32 v5, v5, v4
	v_mul_hi_u32 v5, v4, v5
	v_add_u32_e32 v4, v4, v5
	v_mul_hi_u32 v4, v3, v4
	v_mul_lo_u32 v5, v4, v2
	v_sub_u32_e32 v3, v3, v5
	v_add_u32_e32 v7, 1, v4
	v_cmp_ge_u32_e32 vcc, v3, v2
	v_sub_u32_e32 v5, v3, v2
	s_nop 0
	v_cndmask_b32_e32 v4, v4, v7, vcc
	v_cndmask_b32_e32 v3, v3, v5, vcc
	v_add_u32_e32 v5, 1, v4
	v_cmp_ge_u32_e32 vcc, v3, v2
	s_nop 1
	v_cndmask_b32_e32 v4, v4, v5, vcc
	v_mul_lo_u32 v3, v2, v4
	v_add_u32_e32 v2, v3, v2
	v_cmp_ne_u32_e32 vcc, v6, v2
	v_mov_b64_e32 v[2:3], s[6:7]
	s_and_saveexec_b64 s[4:5], vcc
	s_cbranch_execz .LBB0_290
	s_mov_b64 s[12:13], 0
	s_branch .Lsplit3_ld
	v_mov_b32_e32 v2, 0
	global_load_dword v3, v2, s[6:7] sc1
	s_mov_b64 s[12:13], 0
	s_waitcnt vmcnt(0)
	v_cmp_eq_u32_e32 vcc, v3, v4
	s_and_saveexec_b64 s[10:11], vcc
	s_cbranch_execz .LBB0_289
	s_add_u32 s8, s82, 0x4200
	s_addc_u32 s9, s83, 0
	s_mov_b32 s22, 1
	s_branch .LBB0_282

.LBB0_295:
	s_or_b64 exec, exec, s[0:1]
	v_mov_b32_e32 v12, v0
	s_waitcnt lgkmcnt(0)
	s_barrier
	s_mov_b64 s[100:101], exec
	v_readlane_b32 s98, v254, 6
	s_nop 3
	s_mov_b32 exec_lo, s98
	s_mov_b32 exec_hi, 0
	s_cbranch_execz .Lp3dep_join
	s_and_b32 s98, s64, 127
	s_lshr_b32 s98, s98, 1
	s_max_u32 s99, s98, 1
	s_add_i32 s99, s99, -1
	s_lshl_b32 s98, s98, 8
	s_lshl_b32 s99, s99, 8
	s_add_i32 s98, s98, 0x8000
	s_add_i32 s99, s99, 0x8000
	v_mov_b32_e32 v240, s98
	v_mov_b32_e32 v241, s99
	v_mov_b32_e32 v244, 0
.Lp3dep_spin:
	global_load_dword v242, v240, s[82:83] sc1
	global_load_dword v243, v241, s[82:83] sc1
	s_waitcnt vmcnt(0)
	v_add_u32_e32 v244, 1, v244
	v_readfirstlane_b32 s98, v242
	v_readfirstlane_b32 s99, v243
	s_nop 3
	s_cmp_lt_u32 s98, 6
	s_cbranch_scc1 .Lp3dep_more
	s_cmp_ge_u32 s99, 6
	s_cbranch_scc1 .Lp3dep_join

.Lp3dep_join:
	s_mov_b64 exec, s[100:101]
	s_barrier
	s_nop 0
	v_readfirstlane_b32 s8, v12
	s_ashr_i32 s33, s8, 8
	s_bfe_u32 s18, s8, 0x20006
	s_add_u32 s76, s82, 0x1000000
	s_mul_i32 s0, s33, 0x11400
	s_addc_u32 s77, s83, 0
	v_mov_b32_e32 v14, s0
	s_cmpk_lt_i32 s64, 0x200
	v_and_b32_e32 v169, 63, v12
	s_cselect_b64 s[0:1], -1, 0
	v_add_u32_e32 v13, 0xd000, v14
	s_cmpk_gt_i32 s64, 0x1ff
	v_lshrrev_b32_e32 v15, 2, v12
	s_cbranch_scc1 .LBB0_310
	s_lshl_b32 s2, s64, 1
	s_add_i32 s2, s33, s2
	s_ashr_i32 s4, s2, 8
	s_lshl_b32 s2, s2, 6
	s_and_b32 s5, s2, 0x3fc0
	s_lshl_b32 s2, s4, 7
	s_ashr_i32 s3, s2, 31
	v_and_b32_e32 v2, 60, v15
	s_lshl_b64 s[2:3], s[2:3], 1
	v_or_b32_e32 v4, s5, v2
	s_add_u32 s2, s76, s2
	v_lshlrev_b32_e32 v2, 4, v12
	v_mov_b32_e32 v83, 0
	s_addc_u32 s3, s77, s3
	v_and_b32_e32 v82, 0xf0, v2
	v_mov_b32_e32 v84, v83
	v_mov_b32_e32 v85, v83
	v_add_u32_e32 v16, -3, v4
	v_lshl_add_u64 v[2:3], s[2:3], 0, v[82:83]
	v_mov_b32_e32 v82, v83
	v_mov_b64_e32 v[88:89], v[84:85]
	v_cmp_lt_i32_e32 vcc, -1, v16
	v_mov_b64_e32 v[86:87], v[82:83]
	s_and_saveexec_b64 s[2:3], vcc
	s_cbranch_execz .LBB0_298
	s_movk_i32 s6, 0xc00
	v_mad_u64_u32 v[6:7], s[6:7], v16, s6, v[2:3]
	global_load_dwordx4 v[86:89], v[6:7], off

.LBB0_446:
	s_or_b64 exec, exec, s[6:7]
	v_mov_b32_e32 v253, 0x7000
	global_load_dword v253, v253, s[82:83] offset:1280 sc1
	v_cvt_f32_u32_e32 v6, v4
	s_waitcnt vmcnt(0)
	v_readfirstlane_b32 s4, v5
	v_sub_u32_e32 v5, 0, v4
	v_rcp_iflag_f32_e32 v6, v6
	v_add_u32_e32 v7, s4, v3
	v_mul_f32_e32 v6, 0x4f7ffffe, v6
	v_cvt_u32_f32_e32 v6, v6
	v_mul_lo_u32 v3, v5, v6
	v_mul_hi_u32 v3, v6, v3
	v_add_u32_e32 v3, v6, v3
	v_mul_hi_u32 v3, v7, v3
	v_mul_lo_u32 v5, v3, v4
	v_sub_u32_e32 v5, v7, v5
	v_add_u32_e32 v6, 1, v3
	v_cmp_ge_u32_e32 vcc, v5, v4
	s_nop 1
	v_cndmask_b32_e32 v3, v3, v6, vcc
	v_sub_u32_e32 v6, v5, v4
	v_cndmask_b32_e32 v5, v5, v6, vcc
	v_add_u32_e32 v6, 1, v3
	v_cmp_ge_u32_e32 vcc, v5, v4
	v_add_u32_e32 v5, 1, v7
	s_nop 0
	v_cndmask_b32_e32 v3, v3, v6, vcc
	v_mul_lo_u32 v6, v4, v3
	v_add_u32_e32 v4, v6, v4
	v_cmp_ne_u32_e32 vcc, v5, v4
	s_and_saveexec_b64 s[4:5], vcc
	s_xor_b64 s[4:5], exec, s[4:5]
	s_cbranch_execz .LBB0_460
	s_waitcnt lgkmcnt(0)
	v_mov_b32_e32 v2, 0x7000
	buffer_inv sc1
	s_cmpk_gt_u32 s64, 0x7f
	s_cbranch_scc0 .Lb3chk_noN
.Lb3chk_spinN:
	v_readfirstlane_b32 s99, v253
	s_nop 3
	s_cmp_ge_u32 s99, 3
	s_cbranch_scc1 .Lsplit4_nl
	s_sleep 1
	v_mov_b32_e32 v253, 0x7000
	global_load_dword v253, v253, s[82:83] offset:1280 sc1
	s_waitcnt vmcnt(0)
	s_branch .Lb3chk_spinN
.Lb3chk_noN:
	global_load_dword v2, v2, s[82:83] offset:1280 sc1
	s_add_u32 s10, s82, 0x7500
	s_addc_u32 s11, s83, 0
	s_waitcnt vmcnt(0)
	v_cmp_eq_u32_e32 vcc, v2, v3
	s_and_saveexec_b64 s[6:7], vcc
	s_cbranch_execz .LBB0_459
	s_add_u32 s8, s82, 0x4200
	s_addc_u32 s9, s83, 0
	s_mov_b32 s22, 1
	s_mov_b64 s[12:13], 0
	v_mov_b32_e32 v2, 0
	s_branch .LBB0_450

.LBB0_463:
	s_or_b64 exec, exec, s[6:7]
	v_cvt_f32_u32_e32 v5, v2
	s_waitcnt vmcnt(0)
	v_readfirstlane_b32 s4, v4
	s_add_u32 s6, s82, 0x7500
	s_addc_u32 s7, s83, 0
	v_rcp_iflag_f32_e32 v5, v5
	v_add_u32_e32 v3, s4, v3
	v_add_u32_e32 v6, 1, v3
	s_mov_b64 s[8:9], -1
	v_mul_f32_e32 v4, 0x4f7ffffe, v5
	v_cvt_u32_f32_e32 v4, v4
	v_sub_u32_e32 v5, 0, v2
	v_mul_lo_u32 v5, v5, v4
	v_mul_hi_u32 v5, v4, v5
	v_add_u32_e32 v4, v4, v5
	v_mul_hi_u32 v4, v3, v4
	v_mul_lo_u32 v5, v4, v2
	v_sub_u32_e32 v3, v3, v5
	v_add_u32_e32 v7, 1, v4
	v_cmp_ge_u32_e32 vcc, v3, v2
	v_sub_u32_e32 v5, v3, v2
	s_nop 0
	v_cndmask_b32_e32 v4, v4, v7, vcc
	v_cndmask_b32_e32 v3, v3, v5, vcc
	v_add_u32_e32 v5, 1, v4
	v_cmp_ge_u32_e32 vcc, v3, v2
	s_nop 1
	v_cndmask_b32_e32 v4, v4, v5, vcc
	v_mul_lo_u32 v3, v2, v4
	v_add_u32_e32 v2, v3, v2
	v_cmp_ne_u32_e32 vcc, v6, v2
	v_mov_b64_e32 v[2:3], s[6:7]
	s_and_saveexec_b64 s[4:5], vcc
	s_cbranch_execz .LBB0_475
	s_mov_b64 s[12:13], 0
	s_cmpk_gt_u32 s64, 0x7f
	s_cbranch_scc0 .Lb3chk_noL

.Lb3chk_noL:
	v_mov_b32_e32 v2, 0
	global_load_dword v3, v2, s[6:7] sc1
	s_mov_b64 s[12:13], 0
	s_waitcnt vmcnt(0)
	v_cmp_eq_u32_e32 vcc, v3, v4
	s_and_saveexec_b64 s[10:11], vcc
	s_cbranch_execz .LBB0_474
	s_add_u32 s8, s82, 0x4200
	s_addc_u32 s9, s83, 0
	s_mov_b32 s22, 1
	s_branch .LBB0_467
